# hoist serialized gate loads in DSA per-query and stick-breaking epilogues (one wait instead of 8 round trips)
# speedup vs baseline: 1.0833x; 1.0207x over previous
; DI unsigned pk2(float lo, float hi) { f32x2 x = {lo, hi}; return __builtin_bit_cast(unsigned, __builtin_convertvector(x, bf16x2_t)); }
; DI float bflo(unsigned w) { return __uint_as_float(w << 16); }
; DI float bfhi(unsigned w) { return __uint_as_float(w & 0xffff0000u); }
; DI float silu(float x) { return x * frcp(1.0f + fexp2(-x * LOG2E)); }
; template <int MODE>
; DI void dense_unit(const Params& p, int l, int b, int n, LAS unsigned char* lds) {
;     ...
; #pragma unroll
;   for (int et = 0; et < 2; ++et)
; #pragma unroll
;     for (int g = 0; g < 4; ++g) {
;       const int e0 = hd * 64 + 32 * et + 8 * g + 4 * h;
;       const u32x2 gw = *(const u32x2*)(proj + tq * NP + GCOL + e0);
;       u32x2 o; o.x = pk2(y[et][4 * g] * silu(bflo(gw.x)), y[et][4 * g + 1] * silu(bfhi(gw.x))); o.y = pk2(y[et][4 * g + 2] * silu(bflo(gw.y)), y[et][4 * g + 3] * silu(bfhi(gw.y)));
;       *(u32x2*)(ybuf + tq * DM + YCOL + e0) = o;
;     }
.LBB0_361:
	v_or_b32_e32 v38, v120, v100
	s_mov_b64 s[2:3], 0x1f80
	v_ashrrev_i32_e32 v39, 31, v38
	v_lshl_add_u64 v[36:37], v[98:99], 0, s[2:3]
	v_lshlrev_b64 v[40:41], 1, v[38:39]
	v_lshl_add_u64 v[42:43], v[36:37], 0, v[40:41]
	global_load_dwordx2 v[50:51], v[42:43], off
	global_load_dwordx2 v[52:53], v[42:43], off offset:16
	global_load_dwordx2 v[54:55], v[42:43], off offset:32
	global_load_dwordx2 v[56:57], v[42:43], off offset:48
	global_load_dwordx2 v[58:59], v[42:43], off offset:64
	global_load_dwordx2 v[60:61], v[42:43], off offset:80
	global_load_dwordx2 v[62:63], v[42:43], off offset:96
	global_load_dwordx2 v[64:65], v[42:43], off offset:112
	v_lshlrev_b32_e32 v0, 11, v114
	v_lshl_add_u64 v[34:35], s[96:97], 0, v[0:1]
	s_mov_b64 s[2:3], 0x2000600
	v_lshl_add_u64 v[34:35], v[34:35], 0, s[2:3]
	s_mov_b64 s[56:57], s[90:91]
	v_readlane_b32 s90, v250, 15
	s_mov_b64 s[6:7], 0
	s_movk_i32 s58, 0x100
	s_movk_i32 s59, 0x90
	v_readlane_b32 s60, v251, 46
	s_mov_b32 s61, 0x3f2aaaab
	s_mov_b32 s62, 0x3f317218
	s_movk_i32 s63, 0x204
	s_mov_b32 s64, 0x3fb8aa3b
	s_mov_b32 s65, 0xc2ce8ed0
	s_mov_b32 s66, 0xfe5163ab
	s_mov_b32 s67, 0x3c439041
	s_mov_b32 s68, 0xdb629599
	s_mov_b32 s69, 0xf534ddc0
	s_mov_b32 s70, 0xfc2757d1
	s_mov_b32 s71, 0x4e441529
	s_mov_b32 s72, 0xa2f9836e
	s_mov_b32 s73, 0x3fc90fda
	s_mov_b32 s74, 0xbfc90fda
	s_movk_i32 s75, 0x200
	s_mov_b32 s76, 0xc2fc0000
	s_mov_b32 s77, 0xa002000
	v_readlane_b32 s79, v251, 47
	v_readlane_b32 s80, v251, 48
	s_movk_i32 s81, 0x180
	s_movk_i32 s82, 0x1c0
	s_movk_i32 s83, 0x240
	s_movk_i32 s84, 0x190
	v_readlane_b32 s86, v251, 49
	v_readlane_b32 s91, v250, 16
	v_readlane_b32 s52, v251, 60
	v_readlane_b32 s53, v251, 61
	v_readlane_b32 s54, v250, 11
	v_readlane_b32 s55, v250, 12
	v_readlane_b32 s87, v250, 13
	v_readlane_b32 s93, v250, 14
	s_waitcnt vmcnt(0)
	v_mov_b64_e32 v[42:43], v[50:51]
	v_lshlrev_b32_e32 v44, 16, v42
	v_mul_f32_e32 v0, 0xbfb8aa3b, v44
	v_exp_f32_e32 v0, v0
	v_and_b32_e32 v45, 0xffff0000, v42
	v_lshlrev_b32_e32 v42, 16, v43
	v_and_b32_e32 v43, 0xffff0000, v43
	v_add_f32_e32 v0, 1.0, v0
	v_rcp_f32_e32 v46, v0
	v_mul_f32_e32 v0, 0xbfb8aa3b, v45
	v_exp_f32_e32 v0, v0
	s_nop 0
	v_add_f32_e32 v0, 1.0, v0
	v_rcp_f32_e32 v47, v0
	v_mul_f32_e32 v0, 0xbfb8aa3b, v42
	v_exp_f32_e32 v0, v0
	v_pk_mul_f32 v[44:45], v[46:47], v[44:45]
	s_nop 0
	v_pk_mul_f32 v[18:19], v[18:19], v[44:45]
	v_add_f32_e32 v0, 1.0, v0
	v_rcp_f32_e32 v44, v0
	v_mul_f32_e32 v0, 0xbfb8aa3b, v43
	v_exp_f32_e32 v0, v0
	v_cvt_pk_bf16_f32 v18, v18, v19
	v_add_f32_e32 v0, 1.0, v0
	v_rcp_f32_e32 v45, v0
	s_nop 0
	v_pk_mul_f32 v[42:43], v[44:45], v[42:43]
	s_nop 0
	v_pk_mul_f32 v[20:21], v[20:21], v[42:43]
	s_nop 0
	v_cvt_pk_bf16_f32 v19, v20, v21
	v_lshl_add_u64 v[20:21], v[34:35], 0, v[40:41]
	global_store_dwordx2 v[20:21], v[18:19], off
	v_or_b32_e32 v18, 8, v38
	v_ashrrev_i32_e32 v19, 31, v18
	v_lshlrev_b64 v[18:19], 1, v[18:19]
	v_lshl_add_u64 v[20:21], v[36:37], 0, v[18:19]
	v_mov_b64_e32 v[20:21], v[52:53]
	v_lshl_add_u64 v[18:19], v[34:35], 0, v[18:19]
	v_lshlrev_b32_e32 v40, 16, v20
	v_mul_f32_e32 v0, 0xbfb8aa3b, v40
	v_exp_f32_e32 v0, v0
	v_and_b32_e32 v41, 0xffff0000, v20
	v_add_f32_e32 v0, 1.0, v0
	v_rcp_f32_e32 v42, v0
	v_mul_f32_e32 v0, 0xbfb8aa3b, v41
	v_exp_f32_e32 v0, v0
	s_nop 0
	v_add_f32_e32 v0, 1.0, v0
	v_rcp_f32_e32 v43, v0
	s_nop 0
	v_pk_mul_f32 v[40:41], v[42:43], v[40:41]
	s_nop 0
	v_pk_mul_f32 v[22:23], v[22:23], v[40:41]
	s_nop 0
	v_cvt_pk_bf16_f32 v20, v22, v23
	v_lshlrev_b32_e32 v22, 16, v21
	v_mul_f32_e32 v0, 0xbfb8aa3b, v22
	v_exp_f32_e32 v0, v0
	v_and_b32_e32 v23, 0xffff0000, v21
	v_add_f32_e32 v0, 1.0, v0
	v_rcp_f32_e32 v40, v0
	v_mul_f32_e32 v0, 0xbfb8aa3b, v23
	v_exp_f32_e32 v0, v0
	s_nop 0
	v_add_f32_e32 v0, 1.0, v0
	v_rcp_f32_e32 v41, v0
	s_nop 0
	v_pk_mul_f32 v[22:23], v[40:41], v[22:23]
	s_nop 0
	v_pk_mul_f32 v[22:23], v[24:25], v[22:23]
	s_nop 0
	v_cvt_pk_bf16_f32 v21, v22, v23
	global_store_dwordx2 v[18:19], v[20:21], off
	v_or_b32_e32 v18, 16, v38
	v_ashrrev_i32_e32 v19, 31, v18
	v_lshlrev_b64 v[18:19], 1, v[18:19]
	v_lshl_add_u64 v[20:21], v[36:37], 0, v[18:19]
	v_mov_b64_e32 v[20:21], v[54:55]
	v_lshl_add_u64 v[18:19], v[34:35], 0, v[18:19]
	v_lshlrev_b32_e32 v22, 16, v20
	v_mul_f32_e32 v0, 0xbfb8aa3b, v22
	v_exp_f32_e32 v0, v0
	v_and_b32_e32 v23, 0xffff0000, v20
	v_add_f32_e32 v0, 1.0, v0
	v_rcp_f32_e32 v24, v0
	v_mul_f32_e32 v0, 0xbfb8aa3b, v23
	v_exp_f32_e32 v0, v0
	s_nop 0
	v_add_f32_e32 v0, 1.0, v0
	v_rcp_f32_e32 v25, v0
	s_nop 0
	v_pk_mul_f32 v[22:23], v[24:25], v[22:23]
	s_nop 0
	v_pk_mul_f32 v[22:23], v[26:27], v[22:23]
	s_nop 0
	v_cvt_pk_bf16_f32 v20, v22, v23
	v_lshlrev_b32_e32 v22, 16, v21
	v_mul_f32_e32 v0, 0xbfb8aa3b, v22
	v_exp_f32_e32 v0, v0
	v_and_b32_e32 v23, 0xffff0000, v21
	v_add_f32_e32 v0, 1.0, v0
	v_rcp_f32_e32 v24, v0
	v_mul_f32_e32 v0, 0xbfb8aa3b, v23
	v_exp_f32_e32 v0, v0
	s_nop 0
	v_add_f32_e32 v0, 1.0, v0
	v_rcp_f32_e32 v25, v0
	s_nop 0
	v_pk_mul_f32 v[22:23], v[24:25], v[22:23]
	s_nop 0
	v_pk_mul_f32 v[22:23], v[28:29], v[22:23]
	s_nop 0
	v_cvt_pk_bf16_f32 v21, v22, v23
	global_store_dwordx2 v[18:19], v[20:21], off
	v_or_b32_e32 v18, 24, v38
	v_ashrrev_i32_e32 v19, 31, v18
	v_lshlrev_b64 v[18:19], 1, v[18:19]
	v_lshl_add_u64 v[20:21], v[36:37], 0, v[18:19]
	v_mov_b64_e32 v[20:21], v[56:57]
	v_lshl_add_u64 v[18:19], v[34:35], 0, v[18:19]
; DI unsigned pk2(float lo, float hi) { f32x2 x = {lo, hi}; return __builtin_bit_cast(unsigned, __builtin_convertvector(x, bf16x2_t)); }
; DI float bflo(unsigned w) { return __uint_as_float(w << 16); }
; DI float bfhi(unsigned w) { return __uint_as_float(w & 0xffff0000u); }
; DI float silu(float x) { return x * frcp(1.0f + fexp2(-x * LOG2E)); }
; template <int MODE>
; DI void dense_unit(const Params& p, int l, int b, int n, LAS unsigned char* lds) {
;     ...
; #pragma unroll
;   for (int et = 0; et < 2; ++et)
; #pragma unroll
;     for (int g = 0; g < 4; ++g) {
;       const int e0 = hd * 64 + 32 * et + 8 * g + 4 * h;
;       const u32x2 gw = *(const u32x2*)(proj + tq * NP + GCOL + e0);
;       u32x2 o; o.x = pk2(y[et][4 * g] * silu(bflo(gw.x)), y[et][4 * g + 1] * silu(bfhi(gw.x))); o.y = pk2(y[et][4 * g + 2] * silu(bflo(gw.y)), y[et][4 * g + 3] * silu(bfhi(gw.y)));
;       *(u32x2*)(ybuf + tq * DM + YCOL + e0) = o;
;     }
	v_lshlrev_b32_e32 v22, 16, v20
	v_mul_f32_e32 v0, 0xbfb8aa3b, v22
	v_exp_f32_e32 v0, v0
	v_and_b32_e32 v23, 0xffff0000, v20
	v_add_f32_e32 v0, 1.0, v0
	v_rcp_f32_e32 v24, v0
	v_mul_f32_e32 v0, 0xbfb8aa3b, v23
	v_exp_f32_e32 v0, v0
	s_nop 0
	v_add_f32_e32 v0, 1.0, v0
	v_rcp_f32_e32 v25, v0
	s_nop 0
	v_pk_mul_f32 v[22:23], v[24:25], v[22:23]
	s_nop 0
	v_pk_mul_f32 v[22:23], v[30:31], v[22:23]
	s_nop 0
	v_cvt_pk_bf16_f32 v20, v22, v23
	v_lshlrev_b32_e32 v22, 16, v21
	v_mul_f32_e32 v0, 0xbfb8aa3b, v22
	v_exp_f32_e32 v0, v0
	v_and_b32_e32 v23, 0xffff0000, v21
	v_add_f32_e32 v0, 1.0, v0
	v_rcp_f32_e32 v24, v0
	v_mul_f32_e32 v0, 0xbfb8aa3b, v23
	v_exp_f32_e32 v0, v0
	s_nop 0
	v_add_f32_e32 v0, 1.0, v0
	v_rcp_f32_e32 v25, v0
	s_nop 0
	v_pk_mul_f32 v[22:23], v[24:25], v[22:23]
	s_nop 0
	v_pk_mul_f32 v[22:23], v[32:33], v[22:23]
	s_nop 0
	v_cvt_pk_bf16_f32 v21, v22, v23
	global_store_dwordx2 v[18:19], v[20:21], off
	v_or_b32_e32 v18, 32, v38
	v_ashrrev_i32_e32 v19, 31, v18
	v_lshlrev_b64 v[18:19], 1, v[18:19]
	v_lshl_add_u64 v[20:21], v[36:37], 0, v[18:19]
	v_mov_b64_e32 v[20:21], v[58:59]
	v_lshlrev_b32_e32 v22, 16, v20
	v_mul_f32_e32 v0, 0xbfb8aa3b, v22
	v_exp_f32_e32 v0, v0
	v_and_b32_e32 v23, 0xffff0000, v20
	v_lshlrev_b32_e32 v20, 16, v21
	v_and_b32_e32 v21, 0xffff0000, v21
	v_add_f32_e32 v0, 1.0, v0
	v_rcp_f32_e32 v24, v0
	v_mul_f32_e32 v0, 0xbfb8aa3b, v23
	v_exp_f32_e32 v0, v0
	s_nop 0
	v_add_f32_e32 v0, 1.0, v0
	v_rcp_f32_e32 v25, v0
	v_mul_f32_e32 v0, 0xbfb8aa3b, v20
	v_exp_f32_e32 v0, v0
	v_pk_mul_f32 v[22:23], v[24:25], v[22:23]
	s_nop 0
	v_pk_mul_f32 v[2:3], v[2:3], v[22:23]
	v_add_f32_e32 v0, 1.0, v0
	v_rcp_f32_e32 v22, v0
	v_mul_f32_e32 v0, 0xbfb8aa3b, v21
	v_exp_f32_e32 v0, v0
	v_cvt_pk_bf16_f32 v2, v2, v3
	v_add_f32_e32 v0, 1.0, v0
	v_rcp_f32_e32 v23, v0
	s_nop 0
	v_pk_mul_f32 v[20:21], v[22:23], v[20:21]
	s_nop 0
	v_pk_mul_f32 v[4:5], v[4:5], v[20:21]
	s_nop 0
	v_cvt_pk_bf16_f32 v3, v4, v5
	v_lshl_add_u64 v[4:5], v[34:35], 0, v[18:19]
	global_store_dwordx2 v[4:5], v[2:3], off
	v_or_b32_e32 v2, 40, v38
	v_ashrrev_i32_e32 v3, 31, v2
	v_lshlrev_b64 v[2:3], 1, v[2:3]
	v_lshl_add_u64 v[4:5], v[36:37], 0, v[2:3]
	v_mov_b64_e32 v[4:5], v[60:61]
	v_lshl_add_u64 v[2:3], v[34:35], 0, v[2:3]
	v_lshlrev_b32_e32 v18, 16, v4
	v_mul_f32_e32 v0, 0xbfb8aa3b, v18
	v_exp_f32_e32 v0, v0
	v_and_b32_e32 v19, 0xffff0000, v4
	v_add_f32_e32 v0, 1.0, v0
	v_rcp_f32_e32 v20, v0
	v_mul_f32_e32 v0, 0xbfb8aa3b, v19
	v_exp_f32_e32 v0, v0
	s_nop 0
	v_add_f32_e32 v0, 1.0, v0
	v_rcp_f32_e32 v21, v0
	s_nop 0
	v_pk_mul_f32 v[18:19], v[20:21], v[18:19]
	s_nop 0
	v_pk_mul_f32 v[6:7], v[6:7], v[18:19]
	s_nop 0
	v_cvt_pk_bf16_f32 v4, v6, v7
	v_lshlrev_b32_e32 v6, 16, v5
	v_mul_f32_e32 v0, 0xbfb8aa3b, v6
	v_exp_f32_e32 v0, v0
	v_and_b32_e32 v7, 0xffff0000, v5
	v_add_f32_e32 v0, 1.0, v0
	v_rcp_f32_e32 v18, v0
	v_mul_f32_e32 v0, 0xbfb8aa3b, v7
	v_exp_f32_e32 v0, v0
	s_nop 0
	v_add_f32_e32 v0, 1.0, v0
	v_rcp_f32_e32 v19, v0
	s_nop 0
	v_pk_mul_f32 v[6:7], v[18:19], v[6:7]
	s_nop 0
	v_pk_mul_f32 v[6:7], v[8:9], v[6:7]
	s_nop 0
	v_cvt_pk_bf16_f32 v5, v6, v7
	global_store_dwordx2 v[2:3], v[4:5], off
	v_or_b32_e32 v2, 48, v38
	v_ashrrev_i32_e32 v3, 31, v2
	v_lshlrev_b64 v[2:3], 1, v[2:3]
	v_lshl_add_u64 v[4:5], v[36:37], 0, v[2:3]
	v_mov_b64_e32 v[4:5], v[62:63]
	v_lshl_add_u64 v[2:3], v[34:35], 0, v[2:3]
	v_lshlrev_b32_e32 v6, 16, v4
	v_mul_f32_e32 v0, 0xbfb8aa3b, v6
	v_exp_f32_e32 v0, v0
	v_and_b32_e32 v7, 0xffff0000, v4
	v_add_f32_e32 v0, 1.0, v0
	v_rcp_f32_e32 v8, v0
	v_mul_f32_e32 v0, 0xbfb8aa3b, v7
	v_exp_f32_e32 v0, v0
	s_nop 0
	v_add_f32_e32 v0, 1.0, v0
	v_rcp_f32_e32 v9, v0
	s_nop 0
	v_pk_mul_f32 v[6:7], v[8:9], v[6:7]
	s_nop 0
	v_pk_mul_f32 v[6:7], v[10:11], v[6:7]
	s_nop 0
	v_cvt_pk_bf16_f32 v4, v6, v7
	v_lshlrev_b32_e32 v6, 16, v5
	v_mul_f32_e32 v0, 0xbfb8aa3b, v6
	v_exp_f32_e32 v0, v0
	v_and_b32_e32 v7, 0xffff0000, v5
	v_add_f32_e32 v0, 1.0, v0
	v_rcp_f32_e32 v8, v0
	v_mul_f32_e32 v0, 0xbfb8aa3b, v7
	v_exp_f32_e32 v0, v0
	s_nop 0
	v_add_f32_e32 v0, 1.0, v0
	v_rcp_f32_e32 v9, v0
	s_nop 0
	v_pk_mul_f32 v[6:7], v[8:9], v[6:7]
	s_nop 0
	v_pk_mul_f32 v[6:7], v[12:13], v[6:7]
	s_nop 0
	v_cvt_pk_bf16_f32 v5, v6, v7
	global_store_dwordx2 v[2:3], v[4:5], off
	v_or_b32_e32 v2, 56, v38
	v_ashrrev_i32_e32 v3, 31, v2
	v_lshlrev_b64 v[2:3], 1, v[2:3]
	v_lshl_add_u64 v[4:5], v[36:37], 0, v[2:3]
	v_mov_b64_e32 v[4:5], v[64:65]
	v_lshl_add_u64 v[2:3], v[34:35], 0, v[2:3]
	v_lshlrev_b32_e32 v6, 16, v4
	v_mul_f32_e32 v0, 0xbfb8aa3b, v6
	v_exp_f32_e32 v0, v0
	v_and_b32_e32 v7, 0xffff0000, v4
	v_add_f32_e32 v0, 1.0, v0
	v_rcp_f32_e32 v8, v0
	v_mul_f32_e32 v0, 0xbfb8aa3b, v7
	v_exp_f32_e32 v0, v0
	s_nop 0
	v_add_f32_e32 v0, 1.0, v0
	v_rcp_f32_e32 v9, v0
	s_nop 0
	v_pk_mul_f32 v[6:7], v[8:9], v[6:7]
	s_nop 0
	v_pk_mul_f32 v[6:7], v[14:15], v[6:7]
	s_nop 0
	v_cvt_pk_bf16_f32 v4, v6, v7
	v_lshlrev_b32_e32 v6, 16, v5
	v_mul_f32_e32 v0, 0xbfb8aa3b, v6
	v_exp_f32_e32 v0, v0
	v_and_b32_e32 v7, 0xffff0000, v5
	v_add_f32_e32 v0, 1.0, v0
	v_rcp_f32_e32 v8, v0
	v_mul_f32_e32 v0, 0xbfb8aa3b, v7
	v_exp_f32_e32 v0, v0
	s_nop 0
	v_add_f32_e32 v0, 1.0, v0
	v_rcp_f32_e32 v9, v0
	s_nop 0
	v_pk_mul_f32 v[6:7], v[8:9], v[6:7]
	s_nop 0
	v_pk_mul_f32 v[6:7], v[16:17], v[6:7]
	s_nop 0
	v_cvt_pk_bf16_f32 v5, v6, v7
	global_store_dwordx2 v[2:3], v[4:5], off

; DI unsigned pk2(float lo, float hi) { f32x2 x = {lo, hi}; return __builtin_bit_cast(unsigned, __builtin_convertvector(x, bf16x2_t)); }
; DI float bflo(unsigned w) { return __uint_as_float(w << 16); }
; DI float bfhi(unsigned w) { return __uint_as_float(w & 0xffff0000u); }
; DI float silu(float x) { return x * frcp(1.0f + fexp2(-x * LOG2E)); }
; DI float xsum32(float x) { const unsigned u = __float_as_uint(x); const auto r = __builtin_amdgcn_permlane32_swap(u, u, false, false); return __uint_as_float(r[0]) + __uint_as_float(r[1]); }
; DI void dsa_unit(const Params& p, int l, int b, int g32, LAS unsigned char* lds) {
;     ...
;     lsum = xsum32(lsum);
;     if (r < 4) {
;       const float inv = 1.0f / lsum;
; #pragma unroll
;       for (int et = 0; et < 2; ++et)
; #pragma unroll
;         for (int g = 0; g < 4; ++g) {
;           const int e0 = r * 64 + 32 * et + 8 * g + 4 * h;
;           const u32x2 gw = *(const u32x2*)(proj + tq * NP + C_GA + e0);
;           u32x2 ow; ow.x = pk2(o[et][4 * g] * inv * silu(bflo(gw.x)), o[et][4 * g + 1] * inv * silu(bfhi(gw.x))); ow.y = pk2(o[et][4 * g + 2] * inv * silu(bflo(gw.y)), o[et][4 * g + 3] * inv * silu(bfhi(gw.y)));
;           *(u32x2*)(ybuf + tq * DM + e0) = ow;
;         }
.LBB0_961:
	s_or_b64 exec, exec, s[8:9]
	v_mad_u64_u32 v[34:35], s[2:3], v126, s85, 0
	v_mov_b32_e32 v0, v153
	v_mad_i32_i24 v35, v111, s85, v35
	v_mov_b32_e32 v127, v111
	v_permlane32_swap_b32_e32 v153, v0
	s_and_saveexec_b64 s[8:9], s[6:7]
	s_cbranch_execz .LBB0_897
	v_add_f32_e32 v0, v153, v0
	v_div_scale_f32 v36, s[2:3], v0, v0, 1.0
	v_rcp_f32_e32 v37, v36
	v_lshl_add_u64 v[34:35], v[120:121], 0, v[34:35]
	global_load_dwordx2 v[66:67], v[34:35], off offset:1920
	global_load_dwordx2 v[68:69], v[34:35], off offset:1936
	global_load_dwordx2 v[70:71], v[34:35], off offset:1952
	global_load_dwordx2 v[72:73], v[34:35], off offset:1968
	global_load_dwordx2 v[74:75], v[34:35], off offset:1984
	global_load_dwordx2 v[76:77], v[34:35], off offset:2000
	global_load_dwordx2 v[78:79], v[34:35], off offset:2016
	global_load_dwordx2 v[80:81], v[34:35], off offset:2032
	v_fma_f32 v38, -v36, v37, 1.0
	v_fmac_f32_e32 v37, v38, v37
	v_div_scale_f32 v38, vcc, 1.0, v0, 1.0
	v_mul_f32_e32 v39, v38, v37
	v_fma_f32 v40, -v36, v39, v38
	v_fmac_f32_e32 v39, v40, v37
	v_fma_f32 v36, -v36, v39, v38
	v_div_fmas_f32 v36, v36, v37, v39
	v_div_fixup_f32 v0, v36, v0, 1.0
	v_pk_mul_f32 v[18:19], v[18:19], v[0:1] op_sel_hi:[1,0]
	v_pk_mul_f32 v[20:21], v[20:21], v[0:1] op_sel_hi:[1,0]
	v_lshlrev_b64 v[36:37], 11, v[126:127]
	v_pk_mul_f32 v[22:23], v[22:23], v[0:1] op_sel_hi:[1,0]
	v_pk_mul_f32 v[24:25], v[24:25], v[0:1] op_sel_hi:[1,0]
	v_pk_mul_f32 v[26:27], v[26:27], v[0:1] op_sel_hi:[1,0]
	v_pk_mul_f32 v[2:3], v[2:3], v[0:1] op_sel_hi:[1,0]
	v_pk_mul_f32 v[4:5], v[4:5], v[0:1] op_sel_hi:[1,0]
	v_pk_mul_f32 v[6:7], v[6:7], v[0:1] op_sel_hi:[1,0]
	v_pk_mul_f32 v[8:9], v[8:9], v[0:1] op_sel_hi:[1,0]
	s_waitcnt vmcnt(0)
	v_mov_b64_e32 v[38:39], v[66:67]
	v_lshlrev_b32_e32 v40, 16, v38
	v_and_b32_e32 v41, 0xffff0000, v38
	v_mul_f32_e32 v38, 0xbfb8aa3b, v40
	v_exp_f32_e32 v38, v38
	s_nop 0
	v_add_f32_e32 v38, 1.0, v38
	v_rcp_f32_e32 v42, v38
	v_mul_f32_e32 v38, 0xbfb8aa3b, v41
	v_exp_f32_e32 v38, v38
	s_nop 0
	v_add_f32_e32 v38, 1.0, v38
	v_rcp_f32_e32 v43, v38
	s_nop 0
	v_pk_mul_f32 v[40:41], v[42:43], v[40:41]
	s_nop 0
	v_pk_mul_f32 v[18:19], v[18:19], v[40:41]
	s_nop 0
	v_cvt_pk_bf16_f32 v38, v18, v19
	v_lshlrev_b32_e32 v18, 16, v39
	v_and_b32_e32 v19, 0xffff0000, v39
	v_mul_f32_e32 v39, 0xbfb8aa3b, v18
	v_exp_f32_e32 v39, v39
	s_nop 0
	v_add_f32_e32 v39, 1.0, v39
	v_rcp_f32_e32 v40, v39
	v_mul_f32_e32 v39, 0xbfb8aa3b, v19
	v_exp_f32_e32 v39, v39
	s_nop 0
	v_add_f32_e32 v39, 1.0, v39
	v_rcp_f32_e32 v41, v39
	s_nop 0
	v_pk_mul_f32 v[18:19], v[40:41], v[18:19]
	s_nop 0
	v_pk_mul_f32 v[18:19], v[20:21], v[18:19]
	v_mov_b64_e32 v[20:21], v[68:69]
	v_cvt_pk_bf16_f32 v39, v18, v19
	v_lshl_add_u64 v[18:19], v[124:125], 0, v[36:37]
	global_store_dwordx2 v[18:19], v[38:39], off
	v_lshlrev_b32_e32 v36, 16, v20
	v_and_b32_e32 v37, 0xffff0000, v20
	v_mul_f32_e32 v20, 0xbfb8aa3b, v36
	v_exp_f32_e32 v20, v20
	s_nop 0
	v_add_f32_e32 v20, 1.0, v20
	v_rcp_f32_e32 v38, v20
	v_mul_f32_e32 v20, 0xbfb8aa3b, v37
	v_exp_f32_e32 v20, v20
	s_nop 0
	v_add_f32_e32 v20, 1.0, v20
	v_rcp_f32_e32 v39, v20
	s_nop 0
	v_pk_mul_f32 v[36:37], v[38:39], v[36:37]
	s_nop 0
	v_pk_mul_f32 v[22:23], v[22:23], v[36:37]
	s_nop 0
	v_cvt_pk_bf16_f32 v20, v22, v23
	v_lshlrev_b32_e32 v22, 16, v21
	v_and_b32_e32 v23, 0xffff0000, v21
	v_mul_f32_e32 v21, 0xbfb8aa3b, v22
	v_exp_f32_e32 v21, v21
	s_nop 0
	v_add_f32_e32 v21, 1.0, v21
	v_rcp_f32_e32 v36, v21
	v_mul_f32_e32 v21, 0xbfb8aa3b, v23
	v_exp_f32_e32 v21, v21
	s_nop 0
	v_add_f32_e32 v21, 1.0, v21
	v_rcp_f32_e32 v37, v21
	s_nop 0
	v_pk_mul_f32 v[22:23], v[36:37], v[22:23]
	s_nop 0
	v_pk_mul_f32 v[22:23], v[24:25], v[22:23]
	s_nop 0
	v_cvt_pk_bf16_f32 v21, v22, v23
	global_store_dwordx2 v[18:19], v[20:21], off offset:16
	v_mov_b64_e32 v[20:21], v[70:71]
	v_lshlrev_b32_e32 v22, 16, v20
	v_and_b32_e32 v23, 0xffff0000, v20
	v_mul_f32_e32 v20, 0xbfb8aa3b, v22
	v_exp_f32_e32 v20, v20
	s_nop 0
	v_add_f32_e32 v20, 1.0, v20
	v_rcp_f32_e32 v24, v20
	v_mul_f32_e32 v20, 0xbfb8aa3b, v23
	v_exp_f32_e32 v20, v20
	s_nop 0
	v_add_f32_e32 v20, 1.0, v20
	v_rcp_f32_e32 v25, v20
	s_nop 0
	v_pk_mul_f32 v[22:23], v[24:25], v[22:23]
	s_nop 0
	v_pk_mul_f32 v[22:23], v[26:27], v[22:23]
	v_pk_mul_f32 v[26:27], v[28:29], v[0:1] op_sel_hi:[1,0]
	v_cvt_pk_bf16_f32 v20, v22, v23
	v_lshlrev_b32_e32 v22, 16, v21
	v_and_b32_e32 v23, 0xffff0000, v21
	v_mul_f32_e32 v21, 0xbfb8aa3b, v22
	v_exp_f32_e32 v21, v21
	s_nop 0
	v_add_f32_e32 v21, 1.0, v21
	v_rcp_f32_e32 v24, v21
	v_mul_f32_e32 v21, 0xbfb8aa3b, v23
	v_exp_f32_e32 v21, v21
	s_nop 0
	v_add_f32_e32 v21, 1.0, v21
	v_rcp_f32_e32 v25, v21
	s_nop 0
	v_pk_mul_f32 v[22:23], v[24:25], v[22:23]
	s_nop 0
	v_pk_mul_f32 v[22:23], v[26:27], v[22:23]
	v_pk_mul_f32 v[26:27], v[30:31], v[0:1] op_sel_hi:[1,0]
	v_cvt_pk_bf16_f32 v21, v22, v23
	global_store_dwordx2 v[18:19], v[20:21], off offset:32
	v_mov_b64_e32 v[20:21], v[72:73]
	v_lshlrev_b32_e32 v22, 16, v20
; DI unsigned pk2(float lo, float hi) { f32x2 x = {lo, hi}; return __builtin_bit_cast(unsigned, __builtin_convertvector(x, bf16x2_t)); }
; DI float bflo(unsigned w) { return __uint_as_float(w << 16); }
; DI float bfhi(unsigned w) { return __uint_as_float(w & 0xffff0000u); }
; DI float silu(float x) { return x * frcp(1.0f + fexp2(-x * LOG2E)); }
; DI float xsum32(float x) { const unsigned u = __float_as_uint(x); const auto r = __builtin_amdgcn_permlane32_swap(u, u, false, false); return __uint_as_float(r[0]) + __uint_as_float(r[1]); }
; DI void dsa_unit(const Params& p, int l, int b, int g32, LAS unsigned char* lds) {
;     ...
;     lsum = xsum32(lsum);
;     if (r < 4) {
;       const float inv = 1.0f / lsum;
; #pragma unroll
;       for (int et = 0; et < 2; ++et)
; #pragma unroll
;         for (int g = 0; g < 4; ++g) {
;           const int e0 = r * 64 + 32 * et + 8 * g + 4 * h;
;           const u32x2 gw = *(const u32x2*)(proj + tq * NP + C_GA + e0);
;           u32x2 ow; ow.x = pk2(o[et][4 * g] * inv * silu(bflo(gw.x)), o[et][4 * g + 1] * inv * silu(bfhi(gw.x))); ow.y = pk2(o[et][4 * g + 2] * inv * silu(bflo(gw.y)), o[et][4 * g + 3] * inv * silu(bfhi(gw.y)));
;           *(u32x2*)(ybuf + tq * DM + e0) = ow;
;         }
	v_and_b32_e32 v23, 0xffff0000, v20
	v_mul_f32_e32 v20, 0xbfb8aa3b, v22
	v_exp_f32_e32 v20, v20
	s_nop 0
	v_add_f32_e32 v20, 1.0, v20
	v_rcp_f32_e32 v24, v20
	v_mul_f32_e32 v20, 0xbfb8aa3b, v23
	v_exp_f32_e32 v20, v20
	s_nop 0
	v_add_f32_e32 v20, 1.0, v20
	v_rcp_f32_e32 v25, v20
	s_nop 0
	v_pk_mul_f32 v[22:23], v[24:25], v[22:23]
	s_nop 0
	v_pk_mul_f32 v[22:23], v[26:27], v[22:23]
	v_pk_mul_f32 v[26:27], v[32:33], v[0:1] op_sel_hi:[1,0]
	v_cvt_pk_bf16_f32 v20, v22, v23
	v_lshlrev_b32_e32 v22, 16, v21
	v_and_b32_e32 v23, 0xffff0000, v21
	v_mul_f32_e32 v21, 0xbfb8aa3b, v22
	v_exp_f32_e32 v21, v21
	s_nop 0
	v_add_f32_e32 v21, 1.0, v21
	v_rcp_f32_e32 v24, v21
	v_mul_f32_e32 v21, 0xbfb8aa3b, v23
	v_exp_f32_e32 v21, v21
	s_nop 0
	v_add_f32_e32 v21, 1.0, v21
	v_rcp_f32_e32 v25, v21
	s_nop 0
	v_pk_mul_f32 v[22:23], v[24:25], v[22:23]
	s_nop 0
	v_pk_mul_f32 v[22:23], v[26:27], v[22:23]
	s_nop 0
	v_cvt_pk_bf16_f32 v21, v22, v23
	global_store_dwordx2 v[18:19], v[20:21], off offset:48
	v_mov_b64_e32 v[20:21], v[74:75]
	v_lshlrev_b32_e32 v22, 16, v20
	v_and_b32_e32 v23, 0xffff0000, v20
	v_mul_f32_e32 v20, 0xbfb8aa3b, v22
	v_exp_f32_e32 v20, v20
	s_nop 0
	v_add_f32_e32 v20, 1.0, v20
	v_rcp_f32_e32 v24, v20
	v_mul_f32_e32 v20, 0xbfb8aa3b, v23
	v_exp_f32_e32 v20, v20
	s_nop 0
	v_add_f32_e32 v20, 1.0, v20
	v_rcp_f32_e32 v25, v20
	v_lshlrev_b32_e32 v20, 16, v21
	v_and_b32_e32 v21, 0xffff0000, v21
	v_pk_mul_f32 v[22:23], v[24:25], v[22:23]
	s_nop 0
	v_pk_mul_f32 v[2:3], v[2:3], v[22:23]
	s_nop 0
	v_cvt_pk_bf16_f32 v2, v2, v3
	v_mul_f32_e32 v3, 0xbfb8aa3b, v20
	v_exp_f32_e32 v3, v3
	s_nop 0
	v_add_f32_e32 v3, 1.0, v3
	v_rcp_f32_e32 v22, v3
	v_mul_f32_e32 v3, 0xbfb8aa3b, v21
	v_exp_f32_e32 v3, v3
	s_nop 0
	v_add_f32_e32 v3, 1.0, v3
	v_rcp_f32_e32 v23, v3
	s_nop 0
	v_pk_mul_f32 v[20:21], v[22:23], v[20:21]
	s_nop 0
	v_pk_mul_f32 v[4:5], v[4:5], v[20:21]
	s_nop 0
	v_cvt_pk_bf16_f32 v3, v4, v5
	global_store_dwordx2 v[18:19], v[2:3], off offset:64
	v_mov_b64_e32 v[2:3], v[76:77]
	v_lshlrev_b32_e32 v4, 16, v2
	v_and_b32_e32 v5, 0xffff0000, v2
	v_mul_f32_e32 v2, 0xbfb8aa3b, v4
	v_exp_f32_e32 v2, v2
	s_nop 0
	v_add_f32_e32 v2, 1.0, v2
	v_rcp_f32_e32 v20, v2
	v_mul_f32_e32 v2, 0xbfb8aa3b, v5
	v_exp_f32_e32 v2, v2
	s_nop 0
	v_add_f32_e32 v2, 1.0, v2
	v_rcp_f32_e32 v21, v2
	s_nop 0
	v_pk_mul_f32 v[4:5], v[20:21], v[4:5]
	s_nop 0
	v_pk_mul_f32 v[4:5], v[6:7], v[4:5]
	s_nop 0
	v_cvt_pk_bf16_f32 v2, v4, v5
	v_lshlrev_b32_e32 v4, 16, v3
	v_and_b32_e32 v5, 0xffff0000, v3
	v_mul_f32_e32 v3, 0xbfb8aa3b, v4
	v_exp_f32_e32 v3, v3
	s_nop 0
	v_add_f32_e32 v3, 1.0, v3
	v_rcp_f32_e32 v6, v3
	v_mul_f32_e32 v3, 0xbfb8aa3b, v5
	v_exp_f32_e32 v3, v3
	s_nop 0
	v_add_f32_e32 v3, 1.0, v3
	v_rcp_f32_e32 v7, v3
	s_nop 0
	v_pk_mul_f32 v[4:5], v[6:7], v[4:5]
	s_nop 0
	v_pk_mul_f32 v[4:5], v[8:9], v[4:5]
	v_pk_mul_f32 v[8:9], v[10:11], v[0:1] op_sel_hi:[1,0]
	v_cvt_pk_bf16_f32 v3, v4, v5
	global_store_dwordx2 v[18:19], v[2:3], off offset:80
	v_mov_b64_e32 v[2:3], v[78:79]
	v_lshlrev_b32_e32 v4, 16, v2
	v_and_b32_e32 v5, 0xffff0000, v2
	v_mul_f32_e32 v2, 0xbfb8aa3b, v4
	v_exp_f32_e32 v2, v2
	s_nop 0
	v_add_f32_e32 v2, 1.0, v2
	v_rcp_f32_e32 v6, v2
	v_mul_f32_e32 v2, 0xbfb8aa3b, v5
	v_exp_f32_e32 v2, v2
	s_nop 0
	v_add_f32_e32 v2, 1.0, v2
	v_rcp_f32_e32 v7, v2
	s_nop 0
	v_pk_mul_f32 v[4:5], v[6:7], v[4:5]
	s_nop 0
	v_pk_mul_f32 v[4:5], v[8:9], v[4:5]
	v_pk_mul_f32 v[8:9], v[12:13], v[0:1] op_sel_hi:[1,0]
	v_cvt_pk_bf16_f32 v2, v4, v5
	v_lshlrev_b32_e32 v4, 16, v3
	v_and_b32_e32 v5, 0xffff0000, v3
	v_mul_f32_e32 v3, 0xbfb8aa3b, v4
	v_exp_f32_e32 v3, v3
	s_nop 0
	v_add_f32_e32 v3, 1.0, v3
	v_rcp_f32_e32 v6, v3
	v_mul_f32_e32 v3, 0xbfb8aa3b, v5
	v_exp_f32_e32 v3, v3
	s_nop 0
	v_add_f32_e32 v3, 1.0, v3
	v_rcp_f32_e32 v7, v3
	s_nop 0
	v_pk_mul_f32 v[4:5], v[6:7], v[4:5]
	s_nop 0
	v_pk_mul_f32 v[4:5], v[8:9], v[4:5]
	v_pk_mul_f32 v[8:9], v[14:15], v[0:1] op_sel_hi:[1,0]
	v_cvt_pk_bf16_f32 v3, v4, v5
	global_store_dwordx2 v[18:19], v[2:3], off offset:96
	v_mov_b64_e32 v[2:3], v[80:81]
	v_lshlrev_b32_e32 v4, 16, v2
	v_and_b32_e32 v5, 0xffff0000, v2
	v_mul_f32_e32 v2, 0xbfb8aa3b, v4
	v_exp_f32_e32 v2, v2
	s_nop 0
	v_add_f32_e32 v2, 1.0, v2
	v_rcp_f32_e32 v6, v2
	v_mul_f32_e32 v2, 0xbfb8aa3b, v5
	v_exp_f32_e32 v2, v2
	s_nop 0
	v_add_f32_e32 v2, 1.0, v2
	v_rcp_f32_e32 v7, v2
	s_nop 0
	v_pk_mul_f32 v[4:5], v[6:7], v[4:5]
	s_nop 0
	v_pk_mul_f32 v[4:5], v[8:9], v[4:5]
	v_pk_mul_f32 v[8:9], v[16:17], v[0:1] op_sel_hi:[1,0]
	v_cvt_pk_bf16_f32 v2, v4, v5
	v_lshlrev_b32_e32 v4, 16, v3
	v_and_b32_e32 v5, 0xffff0000, v3
	v_mul_f32_e32 v3, 0xbfb8aa3b, v4
	v_mul_f32_e32 v0, 0xbfb8aa3b, v5
	v_exp_f32_e32 v3, v3
	v_exp_f32_e32 v0, v0
	v_add_f32_e32 v3, 1.0, v3
	v_add_f32_e32 v0, 1.0, v0
	v_rcp_f32_e32 v6, v3
	v_rcp_f32_e32 v7, v0
	s_nop 0
	v_pk_mul_f32 v[4:5], v[6:7], v[4:5]
	s_nop 0
	v_pk_mul_f32 v[4:5], v[8:9], v[4:5]
	s_nop 0
	v_cvt_pk_bf16_f32 v3, v4, v5
	global_store_dwordx2 v[18:19], v[2:3], off offset:112
	s_branch .LBB0_897
